# group barrier also at LN1->up seam (layers 0,1,3; the RWKV layer keeps the grid barrier there)
# speedup vs baseline: 1.0113x; 1.0028x over previous
.LBB0_1978:
	v_readlane_b32 s0, v253, 37
	v_readlane_b32 s16, v250, 0
	s_or_b32 s0, s0, 11
	v_readlane_b32 s19, v250, 3
	s_cmp_ge_i32 s0, s19
	v_readlane_b32 s17, v250, 1
	v_readlane_b32 s18, v250, 2
	s_cbranch_scc1 .LBB0_2034
	s_waitcnt vmcnt(0)
	v_readlane_b32 s2, v253, 40
	v_readlane_b32 s3, v253, 41
	s_and_b64 vcc, exec, s[2:3]
	s_waitcnt vmcnt(0) lgkmcnt(0)
	s_barrier
	s_cbranch_vccnz .LBB0_2033
	s_cmp_lg_u32 s101, 0
	s_cbranch_scc1 .Lmy_gchk_3
	s_mov_b32 s101, 2
	s_cmp_lg_u32 s94, 0x100
	s_cbranch_scc1 .Lmy_gchk_3
	v_readlane_b32 s8, v250, 0
	v_readlane_b32 s9, v250, 1
	s_mov_b32 s2, -1
	v_mbcnt_lo_u32_b32 v0, s2, 0
	v_mbcnt_hi_u32_b32 v0, s2, v0
	v_lshlrev_b32_e32 v0, 2, v0
	s_add_u32 s8, s8, 0x60000
	s_addc_u32 s9, s9, 0
	global_load_dword v1, v0, s[8:9] sc0 sc1
	global_load_dword v2, v0, s[8:9] offset:256 sc0 sc1
	global_load_dword v3, v0, s[8:9] offset:512 sc0 sc1
	global_load_dword v4, v0, s[8:9] offset:768 sc0 sc1
	s_waitcnt vmcnt(0)
	v_cmp_ne_u32_e32 vcc, 0, v1
	v_cmp_eq_u32_e64 s[2:3], v1, v2
	v_cmp_eq_u32_e64 s[12:13], v1, v3
	s_and_b64 s[2:3], s[2:3], vcc
	v_cmp_eq_u32_e64 s[8:9], v1, v4
	s_and_b64 s[2:3], s[2:3], s[12:13]
	s_and_b64 s[2:3], s[2:3], s[8:9]
	s_cmp_eq_u64 s[2:3], -1
	s_cbranch_scc0 .Lmy_gchk_3
	s_mov_b32 s101, 1
.Lmy_gchk_3:
	s_mov_b32 s2, -1
	s_nop 0
	v_mbcnt_lo_u32_b32 v0, s2, 0
	v_mbcnt_hi_u32_b32 v0, s2, v0
	s_nop 0
	v_cmp_eq_u32_e32 vcc, 0, v0
	s_and_saveexec_b64 s[16:17], vcc
	s_cbranch_execz .LBB0_2032
	s_cmp_lg_u32 s101, 1
	s_cbranch_scc1 .Lmy_gfull_3
	v_readlane_b32 s2, v253, 37
	v_readlane_b32 s3, v250, 7
	v_readlane_b32 s8, v250, 0
	v_readlane_b32 s9, v250, 1
	s_cmp_eq_u32 s2, 32
	s_cbranch_scc1 .Lmy_gfull_3
	s_lshl_b32 s2, s2, 10
	s_add_i32 s2, s2, 0x3000
	s_and_b32 s3, s3, 63
	s_lshl_b32 s3, s3, 6
	s_add_i32 s2, s2, s3
	s_add_u32 s8, s8, 0x70000
	s_addc_u32 s9, s9, 0
	v_mov_b32_e32 v0, s2
	v_mov_b32_e32 v1, 1
	s_waitcnt vmcnt(0) lgkmcnt(0)
	global_atomic_add v0, v1, s[8:9]
	s_mov_b32 s2, 0
